# mlstm_a3 backward direction: the 32 C^T fragment loads run 8 ahead of their MFMAs (was 24 individually waited loads)
# speedup vs baseline: 1.0043x; 1.0007x over previous
.LBB0_935:
	s_or_b64 exec, exec, s[48:49]
	s_waitcnt vmcnt(0) lgkmcnt(0)
	v_sub_f32_e32 v50, v55, v105
	s_lshl_b64 s[4:5], s[4:5], 15
	v_mul_f32_e32 v91, 0x3fb8aa3b, v50
	v_lshl_add_u64 v[52:53], v[68:69], 0, s[4:5]
	v_lshlrev_b32_e32 v50, 1, v104
	v_mov_b32_e32 v51, v1
	v_mov_b32_e32 v55, v1
	v_mov_b32_e32 v59, v1
	v_mov_b32_e32 v57, v1
	v_mov_b32_e32 v61, v1
	v_mov_b32_e32 v63, v1
	v_mov_b32_e32 v65, v1
	v_lshl_add_u64 v[190:191], v[52:53], 0, v[50:51]
	global_load_dwordx4 v[212:215], v[190:191], off
	v_lshl_add_u64 v[68:69], v[52:53], 0, v[0:1]
	global_load_dwordx4 v[216:219], v[68:69], off
	v_lshl_add_u64 v[190:191], v[52:53], 0, v[54:55]
	global_load_dwordx4 v[220:223], v[190:191], off
	v_lshl_add_u64 v[68:69], v[52:53], 0, v[58:59]
	global_load_dwordx4 v[224:227], v[68:69], off
	v_lshl_add_u64 v[190:191], v[52:53], 0, v[56:57]
	global_load_dwordx4 v[228:231], v[190:191], off
	v_lshl_add_u64 v[68:69], v[52:53], 0, v[60:61]
	global_load_dwordx4 v[232:235], v[68:69], off
	v_lshl_add_u64 v[190:191], v[52:53], 0, v[62:63]
	global_load_dwordx4 v[236:239], v[190:191], off
	v_lshl_add_u64 v[68:69], v[52:53], 0, v[64:65]
	global_load_dwordx4 v[240:243], v[68:69], off
	v_lshl_add_u64 v[190:191], v[52:53], 0, v[50:51]
	global_load_dwordx4 v[244:247], v[190:191], off offset:64
	s_waitcnt vmcnt(8)
	v_mfma_f32_16x16x32_bf16 v[166:169], v[212:215], v[14:17], 0
	v_lshl_add_u64 v[68:69], v[52:53], 0, v[0:1]
	global_load_dwordx4 v[248:251], v[68:69], off offset:64
	s_waitcnt vmcnt(8)
	v_mfma_f32_16x16x32_bf16 v[170:173], v[216:219], v[14:17], 0
	v_lshl_add_u64 v[190:191], v[52:53], 0, v[54:55]
	global_load_dwordx4 v[212:215], v[190:191], off offset:64
	s_waitcnt vmcnt(8)
	v_mfma_f32_16x16x32_bf16 v[174:177], v[220:223], v[14:17], 0
	v_lshl_add_u64 v[68:69], v[52:53], 0, v[58:59]
	global_load_dwordx4 v[216:219], v[68:69], off offset:64
	s_waitcnt vmcnt(8)
	v_mfma_f32_16x16x32_bf16 v[178:181], v[224:227], v[14:17], 0
	v_lshl_add_u64 v[190:191], v[52:53], 0, v[56:57]
	global_load_dwordx4 v[220:223], v[190:191], off offset:64
	s_waitcnt vmcnt(8)
	v_mfma_f32_16x16x32_bf16 v[182:185], v[228:231], v[14:17], 0
	v_lshl_add_u64 v[68:69], v[52:53], 0, v[60:61]
	global_load_dwordx4 v[224:227], v[68:69], off offset:64
	s_waitcnt vmcnt(8)
	v_mfma_f32_16x16x32_bf16 v[186:189], v[232:235], v[14:17], 0
	v_lshl_add_u64 v[190:191], v[52:53], 0, v[62:63]
	global_load_dwordx4 v[228:231], v[190:191], off offset:64
	s_waitcnt vmcnt(8)
	v_mfma_f32_16x16x32_bf16 v[204:207], v[236:239], v[14:17], 0
	v_lshl_add_u64 v[68:69], v[52:53], 0, v[64:65]
	global_load_dwordx4 v[232:235], v[68:69], off offset:64
	s_waitcnt vmcnt(8)
	v_mfma_f32_16x16x32_bf16 v[208:211], v[240:243], v[14:17], 0
	v_lshl_add_u64 v[190:191], v[52:53], 0, v[50:51]
	global_load_dwordx4 v[236:239], v[190:191], off offset:128
	s_waitcnt vmcnt(8)
	v_mfma_f32_16x16x32_bf16 v[166:169], v[244:247], v[10:13], v[166:169]
	v_lshl_add_u64 v[68:69], v[52:53], 0, v[0:1]
	global_load_dwordx4 v[240:243], v[68:69], off offset:128
	s_waitcnt vmcnt(8)
	v_mfma_f32_16x16x32_bf16 v[170:173], v[248:251], v[10:13], v[170:173]
	v_lshl_add_u64 v[190:191], v[52:53], 0, v[54:55]
	global_load_dwordx4 v[244:247], v[190:191], off offset:128
	s_waitcnt vmcnt(8)
	v_mfma_f32_16x16x32_bf16 v[174:177], v[212:215], v[10:13], v[174:177]
	v_lshl_add_u64 v[68:69], v[52:53], 0, v[58:59]
	global_load_dwordx4 v[248:251], v[68:69], off offset:128
	s_waitcnt vmcnt(8)
	v_mfma_f32_16x16x32_bf16 v[178:181], v[216:219], v[10:13], v[178:181]
	v_lshl_add_u64 v[190:191], v[52:53], 0, v[56:57]
	global_load_dwordx4 v[212:215], v[190:191], off offset:128
	s_waitcnt vmcnt(8)
	v_mfma_f32_16x16x32_bf16 v[182:185], v[220:223], v[10:13], v[182:185]
	v_lshl_add_u64 v[68:69], v[52:53], 0, v[60:61]
	global_load_dwordx4 v[216:219], v[68:69], off offset:128
	s_waitcnt vmcnt(8)
	v_mfma_f32_16x16x32_bf16 v[186:189], v[224:227], v[10:13], v[186:189]
	v_lshl_add_u64 v[190:191], v[52:53], 0, v[62:63]
	global_load_dwordx4 v[220:223], v[190:191], off offset:128
	s_waitcnt vmcnt(8)
	v_mfma_f32_16x16x32_bf16 v[204:207], v[228:231], v[10:13], v[204:207]
	v_lshl_add_u64 v[68:69], v[52:53], 0, v[64:65]
	global_load_dwordx4 v[224:227], v[68:69], off offset:128
	s_waitcnt vmcnt(8)
	v_mfma_f32_16x16x32_bf16 v[208:211], v[232:235], v[10:13], v[208:211]
	v_lshl_add_u64 v[190:191], v[52:53], 0, v[50:51]
	global_load_dwordx4 v[228:231], v[190:191], off offset:192
	s_waitcnt vmcnt(8)
	v_mfma_f32_16x16x32_bf16 v[166:169], v[236:239], v[6:9], v[166:169]
	v_lshl_add_u64 v[68:69], v[52:53], 0, v[0:1]
	global_load_dwordx4 v[232:235], v[68:69], off offset:192
	s_waitcnt vmcnt(8)
	v_mfma_f32_16x16x32_bf16 v[170:173], v[240:243], v[6:9], v[170:173]
	v_lshl_add_u64 v[190:191], v[52:53], 0, v[54:55]
	global_load_dwordx4 v[236:239], v[190:191], off offset:192
	s_waitcnt vmcnt(8)
	v_mfma_f32_16x16x32_bf16 v[174:177], v[244:247], v[6:9], v[174:177]
	v_lshl_add_u64 v[68:69], v[52:53], 0, v[58:59]
	global_load_dwordx4 v[240:243], v[68:69], off offset:192
	s_waitcnt vmcnt(8)
	v_mfma_f32_16x16x32_bf16 v[178:181], v[248:251], v[6:9], v[178:181]
	v_lshl_add_u64 v[190:191], v[52:53], 0, v[56:57]
	global_load_dwordx4 v[244:247], v[190:191], off offset:192
	s_waitcnt vmcnt(8)
	v_mfma_f32_16x16x32_bf16 v[182:185], v[212:215], v[6:9], v[182:185]
	v_lshl_add_u64 v[68:69], v[52:53], 0, v[60:61]
	global_load_dwordx4 v[248:251], v[68:69], off offset:192
	s_waitcnt vmcnt(8)
	v_mfma_f32_16x16x32_bf16 v[186:189], v[216:219], v[6:9], v[186:189]
	v_lshl_add_u64 v[190:191], v[52:53], 0, v[62:63]
	global_load_dwordx4 v[212:215], v[190:191], off offset:192
	s_waitcnt vmcnt(8)
	v_mfma_f32_16x16x32_bf16 v[204:207], v[220:223], v[6:9], v[204:207]
	v_lshl_add_u64 v[68:69], v[52:53], 0, v[64:65]
	global_load_dwordx4 v[216:219], v[68:69], off offset:192
	s_waitcnt vmcnt(8)
	v_mfma_f32_16x16x32_bf16 v[208:211], v[224:227], v[6:9], v[208:211]
	s_waitcnt vmcnt(7)
	v_mfma_f32_16x16x32_bf16 v[10:13], v[228:231], v[2:5], v[166:169]
	s_waitcnt vmcnt(6)
	v_mfma_f32_16x16x32_bf16 v[14:17], v[232:235], v[2:5], v[170:173]
	s_waitcnt vmcnt(5)
	v_mfma_f32_16x16x32_bf16 v[50:53], v[236:239], v[2:5], v[174:177]
	s_waitcnt vmcnt(4)
	v_mfma_f32_16x16x32_bf16 v[166:169], v[240:243], v[2:5], v[178:181]
	s_waitcnt vmcnt(3)
	v_mfma_f32_16x16x32_bf16 v[54:57], v[244:247], v[2:5], v[182:185]
	s_waitcnt vmcnt(2)
	v_exp_f32_e32 v0, v91
	v_mfma_f32_16x16x32_bf16 v[58:61], v[248:251], v[2:5], v[186:189]
	s_waitcnt vmcnt(1)
	v_mfma_f32_16x16x32_bf16 v[170:173], v[212:215], v[2:5], v[204:207]
	s_waitcnt vmcnt(0)
	v_mfma_f32_16x16x32_bf16 v[62:65], v[216:219], v[2:5], v[208:211]
	v_mul_f32_e64 v4, v0, v12
	v_mul_f32_e64 v5, v0, v13
	v_pk_mul_f32 v[2:3], v[0:1], v[10:11] op_sel_hi:[0,1]
	v_pk_mul_f32 v[12:13], v[0:1], v[52:53] op_sel_hi:[0,1]
	v_pk_mul_f32 v[8:9], v[0:1], v[16:17] op_sel_hi:[0,1]
	v_pk_mul_f32 v[6:7], v[0:1], v[14:15] op_sel_hi:[0,1]
	v_pk_mul_f32 v[10:11], v[0:1], v[50:51] op_sel_hi:[0,1]
	v_pk_mul_f32 v[16:17], v[0:1], v[168:169] op_sel_hi:[0,1]
	v_pk_mul_f32 v[14:15], v[0:1], v[166:167] op_sel_hi:[0,1]
	v_pk_mul_f32 v[52:53], v[0:1], v[56:57] op_sel_hi:[0,1]
	v_pk_mul_f32 v[50:51], v[0:1], v[54:55] op_sel_hi:[0,1]
	v_pk_mul_f32 v[56:57], v[0:1], v[60:61] op_sel_hi:[0,1]
	v_pk_mul_f32 v[54:55], v[0:1], v[58:59] op_sel_hi:[0,1]
	v_pk_mul_f32 v[60:61], v[0:1], v[172:173] op_sel_hi:[0,1]
	v_pk_mul_f32 v[58:59], v[0:1], v[170:171] op_sel_hi:[0,1]
	v_pk_mul_f32 v[64:65], v[0:1], v[64:65] op_sel_hi:[0,1]
	v_pk_mul_f32 v[62:63], v[0:1], v[62:63] op_sel_hi:[0,1]
	s_and_saveexec_b64 s[4:5], s[42:43]
	s_cbranch_execz .LBB0_939
	v_xor_b32_e32 v68, 0x7f, v89
	v_mad_u32_u24 v68, v68, s21, v90
	v_add_u32_e32 v69, 0xffffee00, v68
	ds_read_b64_tr_b16 v[172:173], v69
	ds_read_b64_tr_b16 v[170:171], v68
	ds_read_b64_tr_b16 v[174:175], v68 offset:32
	v_cvt_pk_bf16_f32 v166, v132, v133
	v_cvt_pk_bf16_f32 v167, v134, v131
	v_cvt_pk_bf16_f32 v168, v156, v158
	v_cvt_pk_bf16_f32 v169, v160, v162
	v_add_u32_e32 v69, 0xffffee20, v68
	ds_read_b64_tr_b16 v[176:177], v69
	s_waitcnt lgkmcnt(2)
	v_mfma_f32_16x16x32_bf16 v[2:5], v[170:173], v[166:169], v[2:5]
	v_add_u32_e32 v69, 0xffffee40, v68
	ds_read_b64_tr_b16 v[170:171], v68 offset:64
	ds_read_b64_tr_b16 v[172:173], v69
	v_add_u32_e32 v69, 0xffffee60, v68
	s_waitcnt lgkmcnt(0)
	v_mfma_f32_16x16x32_bf16 v[10:13], v[170:173], v[166:169], v[10:13]
	ds_read_b64_tr_b16 v[170:171], v68 offset:96
	ds_read_b64_tr_b16 v[172:173], v69
	v_add_u32_e32 v69, 0xffffee80, v68
	s_waitcnt lgkmcnt(0)
	v_mfma_f32_16x16x32_bf16 v[14:17], v[170:173], v[166:169], v[14:17]
	ds_read_b64_tr_b16 v[170:171], v68 offset:128
	ds_read_b64_tr_b16 v[172:173], v69
	v_add_u32_e32 v69, 0xffffeea0, v68
	s_waitcnt lgkmcnt(0)
	v_mfma_f32_16x16x32_bf16 v[50:53], v[170:173], v[166:169], v[50:53]
	ds_read_b64_tr_b16 v[170:171], v68 offset:160
	ds_read_b64_tr_b16 v[172:173], v69
	v_add_u32_e32 v69, 0xffffeec0, v68
	s_waitcnt lgkmcnt(0)
	v_mfma_f32_16x16x32_bf16 v[54:57], v[170:173], v[166:169], v[54:57]
	ds_read_b64_tr_b16 v[170:171], v68 offset:192
	ds_read_b64_tr_b16 v[172:173], v69
	v_add_u32_e32 v69, 0xffffeee0, v68
	s_waitcnt lgkmcnt(0)
	v_mfma_f32_16x16x32_bf16 v[58:61], v[170:173], v[166:169], v[58:61]
	ds_read_b64_tr_b16 v[170:171], v68 offset:224
	ds_read_b64_tr_b16 v[172:173], v69
	v_mfma_f32_16x16x32_bf16 v[6:9], v[174:177], v[166:169], v[6:9]
	s_waitcnt lgkmcnt(0)
	v_mfma_f32_16x16x32_bf16 v[62:65], v[170:173], v[166:169], v[62:65]
	s_or_b64 exec, exec, s[4:5]
	s_and_saveexec_b64 s[4:5], vcc
	s_cbranch_execnz .LBB0_940
